# P4 head loop: small per-head loads issued before the next-head prefetch batch with counted waits; perm ladder deferred to stage 5 behind one counted wait; prefetch unconditional
# speedup vs baseline: 1.0774x; 1.0023x over previous
; #define ZACC(a) do { a[0] = (f32x4){0.f, 0.f, 0.f, 0.f}; a[1] = (f32x4){0.f, 0.f, 0.f, 0.f}; } while (0)
; __device__ __forceinline__ void rwkv_phase_a(const Ctx& C) {
;     ...
;             const float m4 = mu[h * 64 + ci], m5 = mu[512 + h * 64 + ci], m6 = mu[1024 + h * 64 + ci];
;             const float pz = tokb > 0 ? 1.f : 0.f;
;             zmix8(zn[0], pz, m4, rr); zmix8(zn[1], pz, m5, kx); zmix8(zn[2], pz, m6, vx);
;         }
;         {
;             f32x4 aw[2], aa[2], ag[2]; ZACC(aw); ZACC(aa); ZACC(ag);
; #pragma unroll
;             for (int ks = 0; ks < 2; ++ks)
; #pragma unroll
;                 for (int i = 0; i < 2; ++i) {
;                     aw[i] = __builtin_amdgcn_mfma_f32_16x16x32_bf16(Af[0][ks], Bf[0][ks][i], aw[i], 0, 0, 0);
;                     aa[i] = __builtin_amdgcn_mfma_f32_16x16x32_bf16(Af[1][ks], Bf[1][ks][i], aa[i], 0, 0, 0);
;                     ag[i] = __builtin_amdgcn_mfma_f32_16x16x32_bf16(Af[2][ks], Bf[2][ks][i], ag[i], 0, 0, 0);
;                     ag[i] = __builtin_amdgcn_mfma_f32_16x16x32_bf16(Af[3][ks], Bf[3][ks][i], ag[i], 0, 0, 0);
;                 }
;             if (h + 1 < 8) {
;                 const int hn = h + 1;
; #pragma unroll
;                 for (int ks = 0; ks < 2; ++ks)
; #pragma unroll
;                     for (int i = 0; i < 2; ++i) { const int row = hn * 64 + nc0 + 16 * i;
;                         Bf[0][ks][i] = *(const bf16x8*)(wdecT + (size_t)row * 64 + ks * 32 + q * 8); Bf[1][ks][i] = *(const bf16x8*)(waaaT + (size_t)row * 64 + ks * 32 + q * 8);
;                         Bf[2][ks][i] = *(const bf16x8*)(wgateT + (size_t)row * 128 + ks * 32 + q * 8); Bf[3][ks][i] = *(const bf16x8*)(wgateT + (size_t)row * 128 + 64 + ks * 32 + q * 8); }
;                 zload9(zr, tokb, hn * 64 + ci, zn[0]); zload9(zr, tokb, 512 + hn * 64 + ci, zn[1]); zload9(zr, tokb, 1024 + hn * 64 + ci, zn[2]);
;             }
; #pragma unroll
;             for (int i = 0; i < 2; ++i) {
;                 const int ch = nc0 + 16 * i; const float w0c = w0[h * 64 + ch], a0c = a0[h * 64 + ch];
;     ...
;             const float kkc = k_k[h * 64 + ci], kac = k_a[h * 64 + ci], rkc = r_k[h * 64 + ci];
.LBB0_717:
	v_mov_b32_e32 v210, v0
	v_readlane_b32 s40, v254, 6
	v_and_b32_e32 v192, 63, v210
	v_add_u32_e32 v188, s72, v192
	v_readlane_b32 s41, v254, 7
	s_movk_i32 s14, 0x1000
	v_mfma_f32_16x16x32_bf16 v[42:45], v[18:21], v[118:121], 0
	v_lshl_add_u64 v[34:35], v[188:189], 2, s[40:41]
	global_load_dword v223, v[34:35], off
	global_load_dword v222, v[34:35], off offset:2048
	v_add_co_u32_e32 v34, vcc, s14, v34
	v_mfma_f32_16x16x32_bf16 v[42:45], v[26:29], v[126:129], v[42:45]
	s_nop 0
	v_addc_co_u32_e32 v35, vcc, 0, v35, vcc
	global_load_dword v194, v[34:35], off
	v_mfma_f32_16x16x32_bf16 v[34:37], v[2:5], v[98:101], 0
	v_ashrrev_i32_e32 v216, 6, v210
	v_lshlrev_b32_e32 v212, 3, v216
	v_bfe_u32 v211, v210, 4, 2
	s_waitcnt vmcnt(7)
	v_mfma_f32_16x16x32_bf16 v[54:57], v[18:21], v[166:169], 0
	v_and_b32_e32 v209, 15, v210
	v_add_u32_e32 v230, s71, v212
	s_cmp_lg_u32 s16, 0xf40001c
	s_waitcnt vmcnt(5)
	v_mfma_f32_16x16x32_bf16 v[54:57], v[26:29], v[174:177], v[54:57]
	v_lshlrev_b32_e32 v190, 4, v211
	v_readlane_b32 s42, v254, 8
	v_readlane_b32 s43, v254, 9
	v_mfma_f32_16x16x32_bf16 v[150:153], v[6:9], v[106:109], v[34:37]
	v_readlane_b32 s44, v254, 10
	v_readlane_b32 s45, v254, 11
	v_readlane_b32 s46, v254, 12
	v_mfma_f32_16x16x32_bf16 v[34:37], v[22:25], v[122:125], v[42:45]
	v_readlane_b32 s47, v254, 13
	v_readlane_b32 s48, v254, 14
	v_readlane_b32 s49, v254, 15
	v_mfma_f32_16x16x32_bf16 v[38:41], v[10:13], v[110:113], 0
	v_readlane_b32 s50, v254, 16
	v_readlane_b32 s51, v254, 17
	v_readlane_b32 s52, v254, 18
	v_mfma_f32_16x16x32_bf16 v[46:49], v[2:5], v[138:141], 0
	v_readlane_b32 s53, v254, 19
	v_readlane_b32 s54, v254, 20
	v_readlane_b32 s55, v254, 21
	v_mfma_f32_16x16x32_bf16 v[50:53], v[10:13], v[158:161], 0
	v_mfma_f32_16x16x32_bf16 v[182:185], v[30:33], v[130:133], v[34:37]
	v_mfma_f32_16x16x32_bf16 v[34:37], v[22:25], v[170:173], v[54:57]
	v_mfma_f32_16x16x32_bf16 v[154:157], v[14:17], v[114:117], v[38:41]
	v_mfma_f32_16x16x32_bf16 v[102:105], v[6:9], v[142:145], v[46:49]
	v_mfma_f32_16x16x32_bf16 v[134:137], v[14:17], v[162:165], v[50:53]
	s_waitcnt vmcnt(4)
	v_mfma_f32_16x16x32_bf16 v[146:149], v[30:33], v[178:181], v[34:37]
	s_add_i32 s14, s56, s72
	v_add_u32_e32 v196, s14, v209
	v_readlane_b32 s40, v254, 6
	v_readlane_b32 s54, v254, 20
	v_readlane_b32 s55, v254, 21
	v_mov_b32_e32 v197, v189
	v_readlane_b32 s42, v254, 8
	v_readlane_b32 s43, v254, 9
	v_readlane_b32 s52, v254, 18
	v_readlane_b32 s53, v254, 19
	s_mov_b64 s[66:67], s[54:55]
	v_lshlrev_b64 v[98:99], 2, v[196:197]
	v_readlane_b32 s41, v254, 7
	v_readlane_b32 s46, v254, 12
	v_readlane_b32 s47, v254, 13
	s_mov_b64 s[64:65], s[52:53]
	s_mov_b64 s[54:55], s[42:43]
	s_mov_b64 s[58:59], s[46:47]
	v_lshl_add_u64 v[100:101], s[54:55], 0, v[98:99]
	global_load_dword v114, v[100:101], off
	v_lshl_add_u64 v[98:99], s[58:59], 0, v[98:99]
	global_load_dword v115, v[98:99], off
	global_load_dword v121, v[98:99], off offset:64
	v_lshlrev_b32_e32 v138, 2, v211
	v_or_b32_e32 v122, s56, v209
	v_or_b32_e32 v123, s3, v138
	v_mad_u64_u32 v[112:113], s[14:15], v123, s97, v[122:123]
	global_load_dword v113, v[100:101], off offset:64
	v_lshlrev_b32_e32 v130, 2, v188
	v_readlane_b32 s98, v254, 18
	v_readlane_b32 s99, v254, 19
	v_readlane_b32 s100, v254, 20
	v_readlane_b32 s101, v254, 21
	s_nop 4
	global_load_dword v126, v130, s[98:99]
	global_load_dword v127, v130, s[100:101]
	v_readlane_b32 s98, v254, 42
	v_readlane_b32 s99, v254, 43
	s_nop 4
	global_load_dword v128, v130, s[98:99]
	v_readlane_b32 s14, v253, 4
	v_mov_b32_e32 v191, v189
	v_readlane_b32 s15, v253, 5
	v_add_u32_e32 v34, 64, v196
	v_mov_b32_e32 v35, v189
	v_lshl_add_u64 v[36:37], s[14:15], 0, v[190:191]
	v_readlane_b32 s14, v253, 6
	v_add_u32_e32 v44, 0x50, v196
	v_mov_b32_e32 v45, v189
	v_readlane_b32 s15, v253, 7
	v_lshlrev_b64 v[40:41], 7, v[34:35]
	v_lshlrev_b64 v[34:35], 8, v[34:35]
	v_lshlrev_b64 v[46:47], 7, v[44:45]
	v_lshl_add_u64 v[38:39], s[14:15], 0, v[190:191]
	v_lshl_add_u64 v[42:43], v[36:37], 0, v[40:41]
	v_lshl_add_u64 v[34:35], s[12:13], 0, v[34:35]
	v_lshl_add_u64 v[66:67], v[36:37], 0, v[46:47]
	v_lshlrev_b64 v[36:37], 8, v[44:45]
	v_lshl_add_u64 v[40:41], v[38:39], 0, v[40:41]
	v_lshl_add_u64 v[34:35], v[34:35], 0, v[190:191]
	v_lshl_add_u64 v[68:69], v[38:39], 0, v[46:47]
	v_lshl_add_u64 v[36:37], s[12:13], 0, v[36:37]
	v_lshl_add_u64 v[90:91], v[36:37], 0, v[190:191]
	global_load_dwordx4 v[54:57], v[42:43], off
	global_load_dwordx4 v[62:65], v[42:43], off offset:64
	global_load_dwordx4 v[58:61], v[40:41], off
	global_load_dwordx4 v[50:53], v[40:41], off offset:64
	global_load_dwordx4 v[46:49], v[34:35], off
	s_nop 0
	global_load_dwordx4 v[42:45], v[34:35], off offset:64
	global_load_dwordx4 v[38:41], v[34:35], off offset:128
	s_nop 0
	global_load_dwordx4 v[34:37], v[34:35], off offset:192
	s_nop 0
	global_load_dwordx4 v[86:89], v[66:67], off
	global_load_dwordx4 v[82:85], v[66:67], off offset:64
	global_load_dwordx4 v[78:81], v[68:69], off
	global_load_dwordx4 v[74:77], v[68:69], off offset:64
	global_load_dwordx4 v[70:73], v[90:91], off
	s_nop 0
	global_load_dwordx4 v[66:69], v[90:91], off offset:64
	v_max_i32_e32 v1, 1, v230
	v_add_u32_e32 v92, 64, v188
	v_add_u32_e32 v1, -1, v1
	v_mov_b32_e32 v93, v189
	v_mov_b64_e32 v[94:95], s[26:27]
	v_mad_u64_u32 v[94:95], s[14:15], v1, s0, v[94:95]
	v_lshlrev_b64 v[92:93], 1, v[92:93]
	v_lshl_add_u64 v[94:95], v[94:95], 0, v[92:93]
	v_lshl_add_u64 v[92:93], s[26:27], 0, v[92:93]
	v_or_b32_e32 v1, 1, v230
	v_mad_i64_i32 v[198:199], s[14:15], v1, s0, v[92:93]
	v_or_b32_e32 v1, 2, v230
	v_mad_i64_i32 v[200:201], s[14:15], v1, s0, v[92:93]
	v_or_b32_e32 v1, 3, v230
; __device__ __forceinline__ bf16_t f2bf(float f) { return (bf16_t)(pk2(f, 0.f) & 0xffffu); }
; __device__ __forceinline__ float sigmoidf_(float x) { return frcp(1.0f + __expf(-x)); }
; __device__ __forceinline__ void rwkv_phase_a(const Ctx& C) {
;     ...
;                     for (int i = 0; i < 2; ++i) { const int row = hn * 64 + nc0 + 16 * i;
;                         Bf[0][ks][i] = *(const bf16x8*)(wdecT + (size_t)row * 64 + ks * 32 + q * 8); Bf[1][ks][i] = *(const bf16x8*)(waaaT + (size_t)row * 64 + ks * 32 + q * 8);
;                         Bf[2][ks][i] = *(const bf16x8*)(wgateT + (size_t)row * 128 + ks * 32 + q * 8); Bf[3][ks][i] = *(const bf16x8*)(wgateT + (size_t)row * 128 + 64 + ks * 32 + q * 8); }
;                 zload9(zr, tokb, hn * 64 + ci, zn[0]); zload9(zr, tokb, 512 + hn * 64 + ci, zn[1]); zload9(zr, tokb, 1024 + hn * 64 + ci, zn[2]);
;             }
; #pragma unroll
;             for (int i = 0; i < 2; ++i) {
;                 const int ch = nc0 + 16 * i; const float w0c = w0[h * 64 + ch], a0c = a0[h * 64 + ch];
; #pragma unroll
;                 for (int j = 0; j < 4; ++j) {
;                     const int t = mt * 16 + 4 * q + j;
;                     FM(0)[t * MS + ch] = -0.60653065971f * sigmoidf_(w0c + aw[i][j]);
;                     FM(1)[t * MS + ch] = sigmoidf_(a0c + aa[i][j]);
;                     Gg[(size_t)(tok0 + t) * GWD_ + h * 64 + ch] = f2bf(ag[i][j]);
;                 }
;             }
	v_mad_i64_i32 v[202:203], s[14:15], v1, s0, v[92:93]
	v_or_b32_e32 v1, 4, v230
	v_mad_i64_i32 v[204:205], s[14:15], v1, s0, v[92:93]
	v_or_b32_e32 v1, 5, v230
	v_mad_i64_i32 v[206:207], s[14:15], v1, s0, v[92:93]
	v_or_b32_e32 v1, 6, v230
	v_mad_i64_i32 v[232:233], s[14:15], v1, s0, v[92:93]
	global_load_ushort v1, v[206:207], off
	global_load_ushort v191, v[232:233], off
	v_or_b32_e32 v195, 7, v230
	v_mad_i64_i32 v[96:97], s[14:15], v230, s0, v[92:93]
	v_mad_i64_i32 v[234:235], s[14:15], v195, s0, v[92:93]
	global_load_ushort v195, v[234:235], off
	global_load_ushort v197, v[234:235], off offset:1024
	global_load_ushort v208, v[94:95], off
	global_load_ushort v231, v[96:97], off
	global_load_ushort v236, v[198:199], off
	global_load_ushort v237, v[94:95], off offset:1024
	global_load_ushort v238, v[96:97], off offset:1024
	global_load_ushort v239, v[198:199], off offset:1024
	global_load_ushort v240, v[96:97], off offset:2048
	global_load_ushort v241, v[94:95], off offset:2048
	global_load_ushort v242, v[200:201], off
	global_load_ushort v243, v[202:203], off
	global_load_ushort v244, v[204:205], off
	global_load_ushort v245, v[200:201], off offset:1024
	global_load_ushort v246, v[202:203], off offset:1024
	global_load_ushort v247, v[202:203], off offset:2048
	global_load_ushort v248, v[200:201], off offset:2048
	global_load_ushort v249, v[198:199], off offset:2048
	global_load_ushort v250, v[204:205], off offset:1024
	global_load_ushort v251, v[206:207], off offset:1024
	global_load_ushort v252, v[232:233], off offset:1024
	s_nop 0
	global_load_ushort v232, v[232:233], off offset:2048
	s_nop 0
	global_load_ushort v233, v[206:207], off offset:2048
	s_nop 0
	global_load_ushort v207, v[204:205], off offset:2048
	global_load_dwordx4 v[94:97], v[90:91], off offset:128
	s_nop 0
	global_load_dwordx4 v[90:93], v[90:91], off offset:192
	s_nop 0
	global_load_ushort v201, v[234:235], off offset:2048
.LBB0_721:
	v_add_u32_e32 v106, s92, v138
	v_ashrrev_i32_e32 v107, 31, v106
	s_add_u32 s22, s26, s18
	v_add_u32_e32 v108, s93, v138
	v_lshlrev_b64 v[100:101], 10, v[106:107]
	s_addc_u32 s23, s27, s19
	v_ashrrev_i32_e32 v109, 31, v108
	v_lshl_or_b32 v100, v122, 1, v100
	v_add_lshl_u32 v118, s56, v209, 1
	v_add_u32_e32 v110, s94, v138
	v_lshlrev_b64 v[98:99], 10, v[108:109]
	v_lshl_add_u64 v[100:101], s[22:23], 0, v[100:101]
	v_ashrrev_i32_e32 v111, 31, v110
	v_or_b32_e32 v98, v98, v118
	v_add_co_u32_e32 v100, vcc, s6, v100
	v_lshlrev_b64 v[106:107], 10, v[110:111]
	v_lshl_add_u64 v[98:99], s[22:23], 0, v[98:99]
	v_addc_co_u32_e32 v101, vcc, 0, v101, vcc
	v_or_b32_e32 v106, v106, v118
	v_add_co_u32_e32 v98, vcc, s6, v98
	v_lshl_add_u64 v[106:107], s[22:23], 0, v[106:107]
	s_nop 0
	v_addc_co_u32_e32 v99, vcc, 0, v99, vcc
	v_cvt_pk_bf16_f32 v116, v182, s0
	v_cvt_pk_bf16_f32 v117, v183, s0
	v_add_co_u32_e32 v106, vcc, s6, v106
	v_cvt_pk_bf16_f32 v119, v184, s0
	s_nop 0
	v_addc_co_u32_e32 v107, vcc, 0, v107, vcc
	global_store_short v[100:101], v116, off
	global_store_short v[98:99], v117, off
	global_store_short v[106:107], v119, off
	v_lshl_add_u32 v112, v112, 2, 0
	v_cvt_pk_bf16_f32 v120, v185, s0
	v_readlane_b32 s44, v254, 10
	v_readlane_b32 s45, v254, 11
	v_readlane_b32 s48, v254, 14
	v_readlane_b32 s49, v254, 15
	v_readlane_b32 s50, v254, 16
	v_readlane_b32 s51, v254, 17
	s_mov_b64 s[52:53], s[40:41]
	v_readlane_b32 s40, v254, 42
	v_readlane_b32 s41, v254, 43
	s_movk_i32 s14, 0x220
	v_readlane_b32 s46, v254, 48
	v_readlane_b32 s47, v254, 49
	v_readlane_b32 s48, v254, 50
	v_readlane_b32 s44, v254, 46
	v_readlane_b32 s45, v254, 47
	v_readlane_b32 s42, v254, 44
	v_readlane_b32 s43, v254, 45
	v_readlane_b32 s49, v254, 51
	v_readlane_b32 s50, v254, 52
	v_readlane_b32 s51, v254, 53
	v_readlane_b32 s52, v254, 54
	v_readlane_b32 s53, v254, 55
	v_readlane_b32 s54, v254, 56
	v_readlane_b32 s55, v254, 57
	s_waitcnt vmcnt(52)
	v_add_f32_e32 v108, v150, v114
	v_add_f32_e32 v110, v151, v114
	s_waitcnt vmcnt(51)
	v_add_f32_e32 v109, v154, v115
	v_mul_f32_e32 v108, 0xbfb8aa3b, v108
	v_mul_f32_e32 v109, 0xbfb8aa3b, v109
	v_mul_f32_e32 v110, 0xbfb8aa3b, v110
	v_exp_f32_e32 v108, v108
	v_exp_f32_e32 v109, v109
	v_exp_f32_e32 v110, v110
	v_add_f32_e32 v111, v155, v115
	v_add_f32_e32 v116, v152, v114
	v_add_f32_e32 v117, v156, v115
	v_mul_f32_e32 v111, 0xbfb8aa3b, v111
	v_mul_f32_e32 v116, 0xbfb8aa3b, v116
	v_mul_f32_e32 v117, 0xbfb8aa3b, v117
	s_waitcnt vmcnt(49)
; __device__ __forceinline__ bf16_t f2bf(float f) { return (bf16_t)(pk2(f, 0.f) & 0xffffu); }
; __device__ __forceinline__ float sigmoidf_(float x) { return frcp(1.0f + __expf(-x)); }
; __device__ __forceinline__ void rwkv_phase_a(const Ctx& C) {
;     ...
;                 const int ch = nc0 + 16 * i; const float w0c = w0[h * 64 + ch], a0c = a0[h * 64 + ch];
; #pragma unroll
;                 for (int j = 0; j < 4; ++j) {
;                     const int t = mt * 16 + 4 * q + j;
;                     FM(0)[t * MS + ch] = -0.60653065971f * sigmoidf_(w0c + aw[i][j]);
;                     FM(1)[t * MS + ch] = sigmoidf_(a0c + aa[i][j]);
;                     Gg[(size_t)(tok0 + t) * GWD_ + h * 64 + ch] = f2bf(ag[i][j]);
;                 }
;             }
;         }
;         __syncthreads();
;         {
;             float ld[8], av[8], kkv[8], k2[8], cl[8];
;             const float kkc = k_k[h * 64 + ci], kac = k_a[h * 64 + ci], rkc = r_k[h * 64 + ci];
;             float run = 0.f;
; #pragma unroll
;             for (int u = 0; u < 8; ++u) {
;                 const int t = tg8 * 8 + u;
;                 ld[u] = FM(0)[t * MS + ci]; av[u] = FM(1)[t * MS + ci];
;                 const float kr = kx[u] * kkc; const float n2 = wave_sum(kr * kr);
;                 kkv[u] = kr * __builtin_amdgcn_rsqf(fmaxf(n2, 1e-24f));
;                 k2[u] = kx[u] * (1.0f + (av[u] - 1.0f) * kac);
;                 const float bs = wave_sum(rr[u] * k2[u] * rkc);
;                 if (lane == 0) bon[(size_t)(tok0 + t) * 8 + h] = bs;
	v_add_f32_e32 v102, v102, v113
	v_exp_f32_e32 v111, v111
	v_exp_f32_e32 v116, v116
	v_exp_f32_e32 v117, v117
	v_add_f32_e32 v108, 1.0, v108
	v_mul_f32_e32 v102, 0xbfb8aa3b, v102
	v_add_f32_e32 v109, 1.0, v109
	v_add_f32_e32 v110, 1.0, v110
	v_rcp_f32_e32 v108, v108
	v_exp_f32_e32 v102, v102
	v_rcp_f32_e32 v119, v109
	v_rcp_f32_e32 v109, v110
	v_add_f32_e32 v111, 1.0, v111
	v_add_f32_e32 v116, 1.0, v116
	v_add_f32_e32 v117, 1.0, v117
	v_rcp_f32_e32 v110, v111
	v_rcp_f32_e32 v111, v116
	v_rcp_f32_e32 v116, v117
	v_mul_f32_e32 v117, 0xbf1b4598, v108
	v_add_u32_e32 v108, s95, v138
	v_add_f32_e32 v102, 1.0, v102
	v_mul_f32_e32 v124, 0xbf1b4598, v109
	v_ashrrev_i32_e32 v109, 31, v108
	v_rcp_f32_e32 v102, v102
	v_lshlrev_b64 v[108:109], 10, v[108:109]
	v_or_b32_e32 v108, v108, v118
	v_add_f32_e32 v118, v134, v121
	v_mul_f32_e32 v118, 0xbfb8aa3b, v118
	v_add_f32_e32 v103, v103, v113
	v_exp_f32_e32 v118, v118
	v_mul_f32_e32 v102, 0xbf1b4598, v102
	v_mul_f32_e32 v103, 0xbfb8aa3b, v103
	ds_write2_b32 v112, v117, v102 offset1:16
	v_exp_f32_e32 v103, v103
	v_add_f32_e32 v117, v135, v121
	v_mul_f32_e32 v117, 0xbfb8aa3b, v117
	v_exp_f32_e32 v117, v117
	v_add_f32_e32 v118, 1.0, v118
	v_rcp_f32_e32 v118, v118
	v_add_f32_e32 v103, 1.0, v103
	v_rcp_f32_e32 v103, v103
	v_lshl_add_u64 v[108:109], s[22:23], 0, v[108:109]
	v_add_f32_e32 v117, 1.0, v117
	v_add_co_u32_e32 v108, vcc, s6, v108
	v_add_u32_e32 v102, 0x4400, v112
	v_rcp_f32_e32 v117, v117
	v_addc_co_u32_e32 v109, vcc, 0, v109, vcc
	ds_write2_b32 v102, v119, v118 offset1:16
	v_cvt_pk_bf16_f32 v118, v146, s0
	global_store_short v[108:109], v120, off
	global_store_short v[100:101], v118, off offset:32
	v_mul_f32_e32 v100, 0xbf1b4598, v103
	ds_write2_b32 v112, v124, v100 offset0:68 offset1:84
	ds_write2_b32 v102, v110, v117 offset0:68 offset1:84
	v_add_f32_e32 v100, v104, v113
	v_mul_f32_e32 v100, 0xbfb8aa3b, v100
	v_exp_f32_e32 v100, v100
	v_add_f32_e32 v101, v136, v121
	v_mul_f32_e32 v101, 0xbfb8aa3b, v101
	v_exp_f32_e32 v101, v101
	v_add_f32_e32 v100, 1.0, v100
	v_rcp_f32_e32 v100, v100
	v_cvt_pk_bf16_f32 v103, v147, s0
	v_add_f32_e32 v101, 1.0, v101
	v_rcp_f32_e32 v101, v101
	v_mul_f32_e32 v111, 0xbf1b4598, v111
	global_store_short v[98:99], v103, off offset:32
	v_mul_f32_e32 v98, 0xbf1b4598, v100
	v_add_f32_e32 v114, v153, v114
	ds_write2_b32 v112, v111, v98 offset0:136 offset1:152
	ds_write2_b32 v102, v116, v101 offset0:136 offset1:152
	v_add_f32_e32 v98, v105, v113
	v_mul_f32_e32 v114, 0xbfb8aa3b, v114
	v_mul_f32_e32 v98, 0xbfb8aa3b, v98
	v_add_f32_e32 v115, v157, v115
	v_exp_f32_e32 v114, v114
	v_exp_f32_e32 v98, v98
	v_add_f32_e32 v99, v137, v121
	v_mul_f32_e32 v115, 0xbfb8aa3b, v115
	v_mul_f32_e32 v99, 0xbfb8aa3b, v99
	v_exp_f32_e32 v115, v115
	v_exp_f32_e32 v99, v99
	v_add_f32_e32 v114, 1.0, v114
	v_add_f32_e32 v98, 1.0, v98
	v_rcp_f32_e32 v114, v114
	v_rcp_f32_e32 v98, v98
	v_add_f32_e32 v115, 1.0, v115
	v_add_f32_e32 v99, 1.0, v99
	v_rcp_f32_e32 v115, v115
	v_rcp_f32_e32 v99, v99
	v_mul_f32_e32 v114, 0xbf1b4598, v114
	v_cvt_pk_bf16_f32 v100, v148, s0
	v_mul_f32_e32 v98, 0xbf1b4598, v98
	global_store_short v[106:107], v100, off offset:32
	ds_write2_b32 v112, v114, v98 offset0:204 offset1:220
	ds_write2_b32 v102, v115, v99 offset0:204 offset1:220
	v_cvt_pk_bf16_f32 v98, v149, s0
	global_store_short v[108:109], v98, off offset:32
	v_lshlrev_b64 v[98:99], 2, v[188:189]
	v_lshl_add_u64 v[100:101], s[64:65], 0, v[98:99]
	s_waitcnt lgkmcnt(0)
	s_barrier
	s_waitcnt vmcnt(51)
	v_lshl_add_u64 v[100:101], s[66:67], 0, v[98:99]
	v_mov_b32_e32 v125, v126
	v_lshl_add_u64 v[98:99], s[40:41], 0, v[98:99]
	v_mov_b32_e32 v117, v127
	v_mov_b32_e32 v124, v128
	v_cmp_lt_i32_e32 vcc, 0, v230
	v_lshlrev_b32_e32 v98, 16, v229
	v_and_b32_e32 v99, 0xffff0000, v229
	v_cndmask_b32_e64 v126, 0, 1.0, vcc
	v_fma_f32 v98, v126, v98, -v99
	v_fma_f32 v137, v223, v98, v99
	v_and_b32_e32 v98, 0xffff0000, v219
	v_lshlrev_b32_e32 v102, 16, v228
	v_fma_f32 v98, v126, v98, -v102
	v_fma_f32 v98, v222, v98, v102
	v_mad_u64_u32 v[100:101], s[14:15], v216, s14, v[192:193]
	v_lshl_add_u32 v100, v100, 2, 0
	ds_read2st64_b32 v[100:101], v100 offset1:68
	v_cmp_eq_u32_e32 vcc, 0, v192
	s_nop 0
	v_mul_f32_e32 v127, v98, v125
	v_mul_f32_e32 v103, v127, v127
	s_nop 1
	v_mov_b32_dpp v103, v103 quad_perm:[1,0,3,2] row_mask:0xf bank_mask:0xf
	v_fmac_f32_e32 v103, v127, v127
	v_mov_b32_e32 v104, v103
	s_nop 1
	v_mov_b32_dpp v104, v104 quad_perm:[2,3,0,1] row_mask:0xf bank_mask:0xf
	v_add_f32_e32 v103, v103, v104
	v_mov_b32_e32 v104, v103
	s_nop 1
	v_mov_b32_dpp v104, v104 row_half_mirror row_mask:0xf bank_mask:0xf
	v_add_f32_e32 v103, v103, v104
	v_mov_b32_e32 v104, v103
	s_nop 1
	v_mov_b32_dpp v104, v104 row_mirror row_mask:0xf bank_mask:0xf
	v_add_f32_e32 v103, v103, v104
	s_nop 0
	v_readlane_b32 s21, v103, 0
	v_readlane_b32 s47, v103, 16
	v_readlane_b32 s46, v103, 32
	v_readlane_b32 s48, v103, 48
	s_waitcnt lgkmcnt(0)
	v_add_f32_e32 v103, -1.0, v101
	s_nop 0
	v_fma_f32 v103, v117, v103, 1.0
	v_mul_f32_e32 v98, v98, v103
	v_mul_f32_e32 v103, v137, v98
	s_nop 0
	v_mul_f32_e32 v104, v124, v103
	s_nop 1
	v_mov_b32_dpp v104, v104 quad_perm:[1,0,3,2] row_mask:0xf bank_mask:0xf
	v_fmac_f32_e32 v104, v124, v103
	v_mov_b32_e32 v103, v104
	s_nop 1
	v_mov_b32_dpp v103, v103 quad_perm:[2,3,0,1] row_mask:0xf bank_mask:0xf
	v_add_f32_e32 v103, v104, v103
	v_mov_b32_e32 v104, v103
	s_nop 1
	v_mov_b32_dpp v104, v104 row_half_mirror row_mask:0xf bank_mask:0xf
	v_add_f32_e32 v103, v103, v104
	v_mov_b32_e32 v104, v103
	s_nop 1
	v_mov_b32_dpp v104, v104 row_mirror row_mask:0xf bank_mask:0xf
	v_add_f32_e32 v103, v103, v104
	s_nop 0
	v_readlane_b32 s44, v103, 0
	v_readlane_b32 s14, v103, 16
	v_readlane_b32 s45, v103, 32
	v_readlane_b32 s15, v103, 48
	s_and_saveexec_b64 s[22:23], vcc
	s_cbranch_execz .LBB0_723
	v_add_u32_e32 v104, s31, v212
	v_ashrrev_i32_e32 v105, 31, v104
	s_add_u32 s42, s26, s16
	v_mov_b32_e32 v106, s14
	v_mov_b32_e32 v107, s15
	v_lshlrev_b64 v[104:105], 5, v[104:105]
	s_addc_u32 s43, s27, s17
	v_pk_add_f32 v[106:107], s[44:45], v[106:107]
	v_lshl_add_u64 v[104:105], s[42:43], 0, v[104:105]
	v_add_f32_e32 v103, v106, v107
	global_store_dword v[104:105], v103, off

; __device__ __forceinline__ bf16_t f2bf(float f) { return (bf16_t)(pk2(f, 0.f) & 0xffffu); }
; __device__ __forceinline__ void rwkv_phase_a(const Ctx& C) {
;     ...
;                 const float kr = kx[u] * kkc; const float n2 = wave_sum(kr * kr);
;                 kkv[u] = kr * __builtin_amdgcn_rsqf(fmaxf(n2, 1e-24f));
;                 k2[u] = kx[u] * (1.0f + (av[u] - 1.0f) * kac);
;                 const float bs = wave_sum(rr[u] * k2[u] * rkc);
;                 if (lane == 0) bon[(size_t)(tok0 + t) * 8 + h] = bs;
;                 run += ld[u]; cl[u] = run;
;             }
;             misc[64 + tg8 * 64 + ci] = run;
;             __syncthreads();
;             float pre = 0.f, tot = 0.f;
; #pragma unroll
;             for (int g = 0; g < 8; ++g) { const float v = misc[64 + g * 64 + ci]; tot += v; if (g < tg8) pre += v; }
;             if (tg8 == 0) misc[ci] = __expf(tot);
;             float bh[8], kh[8];
; #pragma unroll
;             for (int u = 0; u < 8; ++u) {
;                 const int t = tg8 * 8 + u; const float cu = cl[u] + pre, cp = cu - ld[u];
;                 const float e_m = __expf(-cu), e_p = __expf(cu), e_t = __expf(tot - cu);
;                 const float at = kkv[u] * __expf(cp);
;                 BM_(0)[t * BS + ci] = f2bf(at); FM(2)[t * MS + ci] = at;
;                 BM_(1)[t * BS + ci] = f2bf(kkv[u] * av[u] * e_m);
;                 BM_(2)[t * BS + ci] = f2bf(k2[u] * e_m);
;                 BM_(3)[t * BS + ci] = f2bf(rr[u] * e_p);
;                 bh[u] = kkv[u] * av[u] * e_t; kh[u] = k2[u] * e_t;
;             }
.LBB0_739:
	s_or_b64 exec, exec, s[22:23]
	v_cmp_lt_i32_e32 vcc, 0, v216
	v_lshlrev_b32_e32 v161, 16, v214
	v_or_b32_e32 v165, s3, v209
	v_cndmask_b32_e32 v160, 0, v160, vcc
	v_add_f32_e32 v159, v159, v160
	v_cmp_lt_i32_e32 vcc, 1, v216
	s_nop 1
	v_cndmask_b32_e32 v159, v160, v159, vcc
	v_add_f32_e32 v158, v158, v159
	v_cmp_lt_i32_e32 vcc, 2, v216
	s_nop 1
	v_cndmask_b32_e32 v158, v159, v158, vcc
	v_add_f32_e32 v157, v157, v158
	v_cmp_lt_i32_e32 vcc, 3, v216
	s_nop 1
	v_cndmask_b32_e32 v157, v158, v157, vcc
	v_add_f32_e32 v156, v156, v157
	v_cmp_lt_i32_e32 vcc, 4, v216
	s_nop 1
	v_cndmask_b32_e32 v156, v157, v156, vcc
	v_add_f32_e32 v135, v135, v156
	v_cmp_lt_i32_e32 vcc, 5, v216
	v_mov_b32_e32 v157, s43
	v_add_f32_e32 v157, s89, v157
	v_cndmask_b32_e32 v135, v156, v135, vcc
	v_add_f32_e32 v134, v134, v135
	v_cmp_lt_i32_e32 vcc, 6, v216
	v_mov_b32_e32 v156, s52
	v_add_f32_e32 v156, s70, v156
	v_cndmask_b32_e32 v134, v135, v134, vcc
	v_add_f32_e32 v124, v124, v134
	v_cmp_lt_i32_e32 vcc, 7, v216
	v_mov_b32_e32 v135, s58
	v_add_f32_e32 v135, s54, v135
	v_cndmask_b32_e32 v164, v134, v124, vcc
	v_mov_b32_e32 v124, s65
	v_mov_b32_e32 v134, s66
	v_add_f32_e32 v124, s59, v124
	v_add_f32_e32 v134, s64, v134
	v_add_f32_e32 v124, v124, v134
	v_mov_b32_e32 v134, s55
	v_add_f32_e32 v134, s53, v134
	v_add_f32_e32 v134, v134, v135
	v_mov_b32_e32 v135, s60
	v_add_f32_e32 v135, s90, v135
	v_add_f32_e32 v135, v135, v156
	v_mov_b32_e32 v156, s42
	v_add_f32_e32 v156, s88, v156
	v_add_f32_e32 v156, v156, v157
	v_max_f32_e32 v124, 0x179abe15, v124
	v_max_f32_e32 v134, 0x179abe15, v134
	v_max_f32_e32 v135, 0x179abe15, v135
	v_max_f32_e32 v156, 0x179abe15, v156
	v_rsq_f32_e32 v124, v124
	v_rsq_f32_e32 v134, v134
	v_rsq_f32_e32 v135, v135
	v_rsq_f32_e32 v156, v156
	v_mul_f32_e32 v125, v125, v124
	v_mul_f32_e32 v124, v133, v134
	v_mul_f32_e32 v135, v132, v135
	v_mul_f32_e32 v134, v131, v156
	v_mov_b32_e32 v131, s14
	v_mov_b32_e32 v132, s15
	v_add_f32_e32 v131, s80, v131
	v_add_f32_e32 v132, s81, v132
	v_add_f32_e32 v131, v131, v132
	v_mov_b32_e32 v132, s78
	v_mov_b32_e32 v133, s79
	v_add_f32_e32 v132, s76, v132
	v_add_f32_e32 v133, s77, v133
	v_add_f32_e32 v132, v132, v133
	v_mov_b32_e32 v133, s74
	v_mov_b32_e32 v156, s75
	v_add_f32_e32 v133, s49, v133
	v_add_f32_e32 v156, s73, v156
	v_add_f32_e32 v133, v133, v156
	v_mov_b32_e32 v156, s47
	v_mov_b32_e32 v157, s48
	v_add_f32_e32 v156, s21, v156
	v_add_f32_e32 v157, s46, v157
	v_add_f32_e32 v156, v156, v157
	v_max_f32_e32 v156, 0x179abe15, v156
	v_max_f32_e32 v133, 0x179abe15, v133
	v_rsq_f32_e32 v158, v156
	v_rsq_f32_e32 v133, v133
	v_max_f32_e32 v131, 0x179abe15, v131
	v_max_f32_e32 v132, 0x179abe15, v132
	v_rsq_f32_e32 v131, v131
	v_rsq_f32_e32 v132, v132
	v_mul_f32_e32 v158, v127, v158
	v_lshlrev_b32_e32 v127, 16, v217
	v_mul_f32_e32 v159, v128, v133
	v_mul_f32_e32 v126, v126, v127
	v_and_b32_e32 v127, 0xffff0000, v217
	v_lshlrev_b32_e32 v128, 16, v213
	v_mov_b32_e32 v162, v127
	v_mov_b32_e32 v163, v128
	v_mul_f32_e32 v157, v130, v131
	v_mul_f32_e32 v156, v129, v132
	v_and_b32_e32 v131, 0xffff0000, v215
	v_lshlrev_b32_e32 v130, 16, v215
	v_and_b32_e32 v129, 0xffff0000, v213
	v_pk_add_f32 v[126:127], v[126:127], v[162:163] neg_lo:[0,1] neg_hi:[0,1]
	v_and_b32_e32 v133, 0xffff0000, v218
	v_pk_fma_f32 v[126:127], v[194:195], v[126:127], v[162:163] op_sel_hi:[0,1,1]
	v_pk_mov_b32 v[162:163], v[128:129], v[130:131] op_sel:[1,0]
	v_lshlrev_b32_e32 v132, 16, v218
	v_pk_add_f32 v[128:129], v[128:129], v[162:163] neg_lo:[0,1] neg_hi:[0,1]
	v_mov_b32_e32 v160, v133
	v_pk_fma_f32 v[128:129], v[194:195], v[128:129], v[162:163] op_sel_hi:[0,1,1]
	v_pk_mov_b32 v[162:163], v[130:131], v[132:133] op_sel:[1,0]
	v_pk_add_f32 v[132:133], v[132:133], v[160:161] neg_lo:[0,1] neg_hi:[0,1]
	v_add_f32_e32 v155, v155, v164
	v_pk_add_f32 v[130:131], v[130:131], v[162:163] neg_lo:[0,1] neg_hi:[0,1]
	v_pk_fma_f32 v[132:133], v[194:195], v[132:133], v[160:161] op_sel_hi:[0,1,1]
	v_sub_f32_e32 v100, v155, v100
	v_mul_f32_e32 v160, 0xbfb8aa3b, v155
	v_pk_fma_f32 v[130:131], v[194:195], v[130:131], v[162:163] op_sel_hi:[0,1,1]
	v_exp_f32_e32 v162, v160
	v_mul_f32_e32 v160, 0x3fb8aa3b, v155
	v_mul_f32_e32 v100, 0x3fb8aa3b, v100
	v_exp_f32_e32 v163, v160
	v_exp_f32_e32 v160, v100
	s_movk_i32 s14, 0x240
	v_mul_lo_u32 v161, v216, s14
	v_or_b32_e32 v161, v161, v192
	v_sub_f32_e32 v100, v149, v155
	v_mul_f32_e32 v155, v158, v160
	v_lshlrev_b32_e32 v166, 1, v161
	v_cvt_pk_bf16_f32 v160, v155, s0
	v_add_u32_e32 v167, 0, v166
	s_movk_i32 s14, 0x880
	ds_write_b16 v167, v160 offset:52224
	v_mad_u64_u32 v[160:161], s[14:15], v216, s14, v[136:137]
	ds_write_b32 v160, v155 offset:34816
	v_mov_b32_e32 v160, v101
	v_mov_b32_e32 v161, v105
	v_pk_mul_f32 v[160:161], v[160:161], v[158:159]
	v_add_u32_e32 v105, s86, v166
	v_mul_f32_e32 v101, v160, v162
	v_cvt_pk_bf16_f32 v101, v101, s0
	ds_write_b16 v167, v101 offset:61440
	v_mul_f32_e32 v101, v98, v162
	v_cvt_pk_bf16_f32 v101, v101, s0
	ds_write_b16 v105, v101
	v_mul_f32_e32 v101, v137, v163
	v_cvt_pk_bf16_f32 v101, v101, s0
	v_add_u32_e32 v105, s87, v166
	ds_write_b16 v105, v101
	v_add_f32_e32 v101, v154, v164
	v_sub_f32_e32 v104, v101, v104
	v_mul_f32_e32 v104, 0x3fb8aa3b, v104
	v_exp_f32_e32 v104, v104
	v_mul_f32_e32 v105, 0xbfb8aa3b, v101
	v_exp_f32_e32 v137, v105
	v_mul_f32_e32 v105, 0x3fb8aa3b, v101
	v_exp_f32_e32 v154, v105
	v_mul_lo_u32 v105, v140, s38
	v_mul_f32_e32 v158, v159, v104
	v_add_lshl_u32 v155, v105, v192, 1
	v_sub_f32_e32 v101, v149, v101
	v_cvt_pk_bf16_f32 v104, v158, s0
	v_add_u32_e32 v159, 0, v155
	v_mul_f32_e32 v100, 0x3fb8aa3b, v100
	v_mul_f32_e32 v101, 0x3fb8aa3b, v101
; #define LAS __attribute__((address_space(3)))
; __device__ __forceinline__ bf16_t f2bf(float f) { return (bf16_t)(pk2(f, 0.f) & 0xffffu); }
; __device__ __forceinline__ u32x4 pack8(const float (&v)[8]) { u32x4 w; w.x = pk2(v[0], v[1]); w.y = pk2(v[2], v[3]); w.z = pk2(v[4], v[5]); w.w = pk2(v[6], v[7]); return w; }
; __device__ __forceinline__ void rwkv_phase_a(const Ctx& C) {
;     ...
;             float bh[8], kh[8];
; #pragma unroll
;             for (int u = 0; u < 8; ++u) {
;                 const int t = tg8 * 8 + u; const float cu = cl[u] + pre, cp = cu - ld[u];
;                 const float e_m = __expf(-cu), e_p = __expf(cu), e_t = __expf(tot - cu);
;                 const float at = kkv[u] * __expf(cp);
;                 BM_(0)[t * BS + ci] = f2bf(at); FM(2)[t * MS + ci] = at;
;                 BM_(1)[t * BS + ci] = f2bf(kkv[u] * av[u] * e_m);
;                 BM_(2)[t * BS + ci] = f2bf(k2[u] * e_m);
;                 BM_(3)[t * BS + ci] = f2bf(rr[u] * e_p);
;                 bh[u] = kkv[u] * av[u] * e_t; kh[u] = k2[u] * e_t;
;             }
;             *(LAS u32x4*)(BM_(4) + ci * BS + tg8 * 8) = pack8(vx);
;             *(LAS u32x4*)(BM_(5) + ci * BS + tg8 * 8) = pack8(bh);
;             *(LAS u32x4*)(BM_(6) + ci * BS + tg8 * 8) = pack8(kh);
;         }
;         __syncthreads();
	ds_write_b16 v159, v104 offset:52224
	v_mad_u64_u32 v[104:105], s[14:15], v140, s39, v[136:137]
	v_exp_f32_e32 v100, v100
	v_exp_f32_e32 v101, v101
	v_mul_f32_e32 v105, v161, v137
	v_cvt_pk_bf16_f32 v105, v105, s0
	ds_write_b16 v159, v105 offset:61440
	v_mul_f32_e32 v105, v99, v137
	v_cvt_pk_bf16_f32 v105, v105, s0
	v_add_u32_e32 v140, s86, v155
	ds_write_b16 v140, v105
	v_mul_f32_e32 v105, v139, v154
	v_add_u32_e32 v139, s87, v155
	v_pk_mul_f32 v[154:155], v[98:99], v[100:101]
	v_add_f32_e32 v98, v153, v164
	v_sub_f32_e32 v99, v98, v106
	v_mul_f32_e32 v99, 0x3fb8aa3b, v99
	v_exp_f32_e32 v99, v99
	v_cvt_pk_bf16_f32 v105, v105, s0
	v_pk_mul_f32 v[136:137], v[160:161], v[100:101]
	v_mul_f32_e32 v100, 0xbfb8aa3b, v98
	ds_write_b16 v139, v105
	v_exp_f32_e32 v105, v100
	v_mul_f32_e32 v100, 0x3fb8aa3b, v98
	v_mul_f32_e32 v99, v156, v99
	v_exp_f32_e32 v106, v100
	v_cvt_pk_bf16_f32 v100, v99, s0
	ds_write_b16 v159, v100 offset:52368
	v_mov_b32_e32 v100, v107
	v_mov_b32_e32 v101, v109
	v_add_u32_e32 v153, 0x8800, v104
	v_pk_mul_f32 v[100:101], v[100:101], v[156:157]
	ds_write2_b32 v153, v158, v99 offset1:68
	v_mul_f32_e32 v99, v100, v105
	v_cvt_pk_bf16_f32 v99, v99, s0
	ds_write_b16 v159, v99 offset:61584
	v_mul_f32_e32 v99, v102, v105
	v_cvt_pk_bf16_f32 v99, v99, s0
	ds_write_b16 v140, v99 offset:144
	v_mul_f32_e32 v99, v141, v106
	v_cvt_pk_bf16_f32 v99, v99, s0
	ds_write_b16 v139, v99 offset:144
	v_add_f32_e32 v99, v152, v164
	v_sub_f32_e32 v105, v99, v108
	v_mul_f32_e32 v105, 0x3fb8aa3b, v105
	v_exp_f32_e32 v105, v105
	v_mul_f32_e32 v106, 0xbfb8aa3b, v99
	v_exp_f32_e32 v106, v106
	v_mul_f32_e32 v107, 0x3fb8aa3b, v99
	v_sub_f32_e32 v98, v149, v98
	v_exp_f32_e32 v107, v107
	v_sub_f32_e32 v99, v149, v99
	v_mul_f32_e32 v105, v157, v105
	v_mul_f32_e32 v98, 0x3fb8aa3b, v98
	v_mul_f32_e32 v99, 0x3fb8aa3b, v99
	v_cvt_pk_bf16_f32 v108, v105, s0
	v_exp_f32_e32 v98, v98
	v_exp_f32_e32 v99, v99
	ds_write_b16 v159, v108 offset:52512
	v_mul_f32_e32 v108, v101, v106
	v_mul_f32_e32 v106, v103, v106
	v_cvt_pk_bf16_f32 v106, v106, s0
	ds_write_b16 v140, v106 offset:288
	v_mul_f32_e32 v106, v142, v107
	v_cvt_pk_bf16_f32 v106, v106, s0
	ds_write_b16 v139, v106 offset:288
	v_pk_mul_f32 v[106:107], v[100:101], v[98:99]
	v_pk_mul_f32 v[102:103], v[102:103], v[98:99]
	v_add_f32_e32 v98, v151, v164
	v_sub_f32_e32 v99, v98, v112
	v_mul_f32_e32 v99, 0x3fb8aa3b, v99
	v_exp_f32_e32 v99, v99
	v_cvt_pk_bf16_f32 v108, v108, s0
	v_mul_f32_e32 v100, 0xbfb8aa3b, v98
	ds_write_b16 v159, v108 offset:61728
	v_exp_f32_e32 v108, v100
	v_mul_f32_e32 v100, 0x3fb8aa3b, v98
	v_mul_f32_e32 v99, v134, v99
	v_exp_f32_e32 v109, v100
	v_cvt_pk_bf16_f32 v100, v99, s0
	ds_write_b16 v159, v100 offset:52656
	ds_write2_b32 v153, v105, v99 offset0:136 offset1:204
	v_mov_b32_e32 v100, v113
	v_mov_b32_e32 v101, v115
	v_pk_mul_f32 v[100:101], v[100:101], v[134:135]
	v_sub_f32_e32 v98, v149, v98
	v_mul_f32_e32 v99, v100, v108
	v_cvt_pk_bf16_f32 v99, v99, s0
	ds_write_b16 v159, v99 offset:61872
	v_mul_f32_e32 v99, v110, v108
	v_cvt_pk_bf16_f32 v99, v99, s0
	ds_write_b16 v140, v99 offset:432
	v_mul_f32_e32 v99, v143, v109
	v_cvt_pk_bf16_f32 v99, v99, s0
	ds_write_b16 v139, v99 offset:432
	v_add_f32_e32 v99, v150, v164
	v_sub_f32_e32 v105, v99, v114
	v_mul_f32_e32 v105, 0x3fb8aa3b, v105
	v_exp_f32_e32 v105, v105
	v_mul_f32_e32 v108, 0xbfb8aa3b, v99
	v_exp_f32_e32 v108, v108
	v_mul_f32_e32 v109, 0x3fb8aa3b, v99
	v_exp_f32_e32 v109, v109
	v_sub_f32_e32 v99, v149, v99
	v_mul_f32_e32 v105, v135, v105
	v_mul_f32_e32 v98, 0x3fb8aa3b, v98
	v_mul_f32_e32 v99, 0x3fb8aa3b, v99
	v_cvt_pk_bf16_f32 v112, v105, s0
	v_exp_f32_e32 v98, v98
	v_exp_f32_e32 v99, v99
	ds_write_b16 v159, v112 offset:52800
	v_mul_f32_e32 v112, v101, v108
	v_mul_f32_e32 v108, v111, v108
	v_cvt_pk_bf16_f32 v108, v108, s0
	ds_write_b16 v140, v108 offset:576
	v_mul_f32_e32 v108, v144, v109
	v_cvt_pk_bf16_f32 v108, v108, s0
	ds_write_b16 v139, v108 offset:576
	v_pk_mul_f32 v[108:109], v[100:101], v[98:99]
	v_pk_mul_f32 v[110:111], v[110:111], v[98:99]
	v_add_f32_e32 v98, v148, v164
	v_sub_f32_e32 v99, v98, v118
	v_mul_f32_e32 v99, 0x3fb8aa3b, v99
	v_exp_f32_e32 v99, v99
	v_cvt_pk_bf16_f32 v112, v112, s0
	v_mul_f32_e32 v100, 0xbfb8aa3b, v98
	ds_write_b16 v159, v112 offset:62016
	v_exp_f32_e32 v112, v100
	v_mul_f32_e32 v100, 0x3fb8aa3b, v98
	v_mul_f32_e32 v99, v124, v99
	v_exp_f32_e32 v113, v100
	v_cvt_pk_bf16_f32 v100, v99, s0
	ds_write_b16 v159, v100 offset:52944
	v_add_u32_e32 v100, 0x8c00, v104
	ds_write2_b32 v100, v105, v99 offset0:16 offset1:84
	v_mov_b32_e32 v100, v119
	v_mov_b32_e32 v101, v121
	v_pk_mul_f32 v[100:101], v[100:101], v[124:125]
	v_sub_f32_e32 v98, v149, v98
	v_mul_f32_e32 v99, v100, v112
	v_cvt_pk_bf16_f32 v99, v99, s0
	ds_write_b16 v159, v99 offset:62160
	v_mul_f32_e32 v99, v116, v112
	v_cvt_pk_bf16_f32 v99, v99, s0
	ds_write_b16 v140, v99 offset:720
	v_mul_f32_e32 v99, v145, v113
	v_cvt_pk_bf16_f32 v99, v99, s0
	ds_write_b16 v139, v99 offset:720
	v_add_f32_e32 v99, v147, v164
	v_sub_f32_e32 v105, v99, v120
	v_mul_f32_e32 v105, 0x3fb8aa3b, v105
	v_exp_f32_e32 v105, v105
	v_mul_f32_e32 v112, 0xbfb8aa3b, v99
	v_exp_f32_e32 v112, v112
	v_mul_f32_e32 v113, 0x3fb8aa3b, v99
	v_mul_f32_e32 v105, v125, v105
	v_cvt_pk_bf16_f32 v114, v105, s0
	v_exp_f32_e32 v113, v113
	v_sub_f32_e32 v99, v149, v99
	ds_write_b16 v159, v114 offset:53088
	ds_write_b32 v104, v105 offset:36448
	v_mul_f32_e32 v104, v101, v112
	v_mul_f32_e32 v98, 0x3fb8aa3b, v98
	v_mul_f32_e32 v99, 0x3fb8aa3b, v99
	v_cvt_pk_bf16_f32 v104, v104, s0
	v_exp_f32_e32 v98, v98
	v_exp_f32_e32 v99, v99
	ds_write_b16 v159, v104 offset:62304
	v_mul_f32_e32 v104, v117, v112
	v_cvt_pk_bf16_f32 v104, v104, s0
	ds_write_b16 v140, v104 offset:864
	v_mul_f32_e32 v104, v146, v113
	v_mul_u32_u24_e32 v114, 0x48, v192
	v_cvt_pk_bf16_f32 v104, v104, s0
	v_lshlrev_b32_e32 v114, 1, v114
	v_lshlrev_b32_e32 v115, 1, v212
	ds_write_b16 v139, v104 offset:864
	v_pk_mul_f32 v[104:105], v[100:101], v[98:99]
	v_pk_mul_f32 v[112:113], v[116:117], v[98:99]
	v_cvt_pk_bf16_f32 v98, v126, v127
	v_cvt_pk_bf16_f32 v99, v128, v129
	v_cvt_pk_bf16_f32 v100, v130, v131
	v_cvt_pk_bf16_f32 v101, v132, v133
	v_add3_u32 v116, s34, v114, v115
	ds_write_b128 v116, v[98:101]
	v_cvt_pk_bf16_f32 v98, v136, v137
	v_cvt_pk_bf16_f32 v99, v106, v107
	v_cvt_pk_bf16_f32 v100, v108, v109
	v_cvt_pk_bf16_f32 v101, v104, v105
	v_add3_u32 v104, s35, v114, v115
	ds_write_b128 v104, v[98:101]
	v_cvt_pk_bf16_f32 v98, v154, v155
	v_cvt_pk_bf16_f32 v99, v102, v103
	v_cvt_pk_bf16_f32 v100, v110, v111
	v_cvt_pk_bf16_f32 v101, v112, v113
	v_add3_u32 v102, s36, v114, v115
	v_mul_lo_u32 v131, v165, s37
	ds_write_b128 v102, v[98:101]
	v_add3_u32 v102, 0, v131, v190
	s_waitcnt lgkmcnt(0)
	s_barrier
; __device__ __forceinline__ bf16_t f2bf(float f) { return (bf16_t)(pk2(f, 0.f) & 0xffffu); }
; #define ZACC(a) do { a[0] = (f32x4){0.f, 0.f, 0.f, 0.f}; a[1] = (f32x4){0.f, 0.f, 0.f, 0.f}; } while (0)
; __device__ __forceinline__ void rwkv_phase_a(const Ctx& C) {
;     ...
;         {
;             f32x4 x1[2], x2[2], x3[2], x4[2]; ZACC(x1); ZACC(x2); ZACC(x3); ZACC(x4);
;             mmb(x1, BM_(0), BM_(2), mrow, nc0, q);
;             mmb(x2, BM_(0), BM_(1), mrow, nc0, q);
;             mmb(x3, BM_(3), BM_(1), mrow, nc0, q);
;             mmb(x4, BM_(3), BM_(2), mrow, nc0, q);
; #pragma unroll
;             for (int i = 0; i < 2; ++i)
; #pragma unroll
;                 for (int j = 0; j < 4; ++j) { const int r = mt * 16 + 4 * q + j, cc = nc0 + 16 * i;
;                     BM_(7)[r * BS + cc] = f2bf(r > cc ? x1[i][j] : 0.f); FM(0)[r * MS + cc] = r > cc ? x2[i][j] : 0.f;
;                     BM_(8)[r * BS + cc] = f2bf(r >= cc ? x3[i][j] : 0.f); BM_(9)[r * BS + cc] = f2bf(r >= cc ? x4[i][j] : 0.f); }
;         }
	ds_read_b128 v[98:101], v102 offset:52224
	v_mul_u32_u24_e32 v110, 0x90, v122
	v_add3_u32 v103, s86, v110, v190
	ds_read_b128 v[104:107], v103
	ds_read_b128 v[112:115], v102 offset:52288
	ds_read_b128 v[116:119], v103 offset:64
	ds_read_b128 v[134:137], v103 offset:2304
	ds_read_b128 v[140:143], v103 offset:2368
	v_mad_u32_u24 v103, v122, s37, 0
	v_add_u32_e32 v132, v103, v190
	ds_read_b128 v[148:151], v132 offset:61440
	ds_read_b128 v[152:155], v132 offset:61504
	ds_read_b128 v[160:163], v132 offset:63744
	ds_read_b128 v[164:167], v132 offset:63808
	s_waitcnt lgkmcnt(8)
	v_mfma_f32_16x16x32_bf16 v[124:127], v[98:101], v[104:107], 0
	v_add3_u32 v108, s87, v131, v190
	v_mul_lo_u32 v109, v123, s38
	v_cmp_gt_u32_e32 vcc, v123, v122
	s_waitcnt lgkmcnt(5)
	v_mfma_f32_16x16x32_bf16 v[144:147], v[98:101], v[134:137], 0
	v_add_lshl_u32 v111, v109, v122, 1
	s_movk_i32 s14, 0xff74
	v_mad_i32_i24 v103, v122, s14, v103
	s_waitcnt lgkmcnt(3)
	v_mfma_f32_16x16x32_bf16 v[156:159], v[98:101], v[148:151], 0
	v_or_b32_e32 v130, 16, v122
	v_add3_u32 v133, s34, v110, v190
	s_waitcnt lgkmcnt(1)
	v_mfma_f32_16x16x32_bf16 v[98:101], v[98:101], v[160:163], 0
	v_mfma_f32_16x16x32_bf16 v[124:127], v[112:115], v[116:119], v[124:127]
	v_mfma_f32_16x16x32_bf16 v[144:147], v[112:115], v[140:143], v[144:147]
	v_mfma_f32_16x16x32_bf16 v[156:159], v[112:115], v[152:155], v[156:159]
	s_waitcnt lgkmcnt(0)
	v_mfma_f32_16x16x32_bf16 v[98:101], v[112:115], v[164:167], v[98:101]
	ds_read_b128 v[112:115], v108
	ds_read_b128 v[168:171], v108 offset:64
	s_nop 1
	v_cvt_pk_bf16_f32 v108, v124, s0
	v_cndmask_b32_e32 v108, 0, v108, vcc
	s_waitcnt lgkmcnt(1)
	v_mfma_f32_16x16x32_bf16 v[148:151], v[112:115], v[148:151], 0
	v_lshl_add_u32 v124, v122, 2, 0
	v_mfma_f32_16x16x32_bf16 v[104:107], v[112:115], v[104:107], 0
	s_waitcnt lgkmcnt(0)
	v_mfma_f32_16x16x32_bf16 v[148:151], v[168:171], v[152:155], v[148:151]
	v_mfma_f32_16x16x32_bf16 v[104:107], v[168:171], v[116:119], v[104:107]
	v_add_u32_e32 v116, s91, v111
	ds_write_b16 v116, v108
	v_mul_lo_u32 v116, v123, s39
	v_cndmask_b32_e32 v108, 0, v156, vcc
	v_add_u32_e32 v117, v103, v116
	ds_write_b32 v117, v108
	s_nop 0
	v_cvt_pk_bf16_f32 v108, v148, s0
	v_cmp_lt_u32_e32 vcc, v123, v122
	v_cvt_pk_bf16_f32 v104, v104, s0
	v_add_u32_e32 v117, s2, v111
	v_cndmask_b32_e64 v108, v108, 0, vcc
	v_cndmask_b32_e64 v104, v104, 0, vcc
	ds_write_b16 v117, v108
	v_add_u32_e32 v108, s68, v111
	ds_write_b16 v108, v104
	v_add_u32_e32 v108, 0x48, v109
	v_cvt_pk_bf16_f32 v104, v125, s0
	v_add_lshl_u32 v111, v108, v122, 1
	v_cndmask_b32_e64 v104, v104, 0, vcc
	v_add_u32_e32 v117, s91, v111
	ds_write_b16 v117, v104
	v_add_u32_e32 v117, 0x110, v116
	v_mfma_f32_16x16x32_bf16 v[160:163], v[112:115], v[160:163], 0
	v_cndmask_b32_e64 v104, v157, 0, vcc
	v_add_u32_e32 v118, v103, v117
	ds_write_b32 v118, v104
	v_mfma_f32_16x16x32_bf16 v[112:115], v[112:115], v[134:137], 0
	v_or_b32_e32 v136, 1, v123
	v_cvt_pk_bf16_f32 v104, v149, s0
	v_cmp_lt_u32_e32 vcc, v136, v122
	v_cvt_pk_bf16_f32 v105, v105, s0
	v_add_u32_e32 v118, s2, v111
	v_cndmask_b32_e64 v104, v104, 0, vcc
	v_cndmask_b32_e64 v105, v105, 0, vcc
	ds_write_b16 v118, v104
	v_add_u32_e32 v104, s68, v111
	v_or_b32_e32 v135, 2, v123
	ds_write_b16 v104, v105
	v_add_u32_e32 v105, 0x90, v109
	v_cvt_pk_bf16_f32 v104, v126, s0
	v_cmp_gt_u32_e32 vcc, v135, v122
	v_add_lshl_u32 v111, v105, v122, 1
	v_add_u32_e32 v118, s91, v111
	v_cndmask_b32_e32 v104, 0, v104, vcc
	ds_write_b16 v118, v104
	v_add_u32_e32 v118, 0x220, v116
	v_cndmask_b32_e32 v104, 0, v158, vcc
	v_add_u32_e32 v119, v103, v118
	ds_write_b32 v119, v104
	v_cvt_pk_bf16_f32 v104, v150, s0
	v_cmp_lt_u32_e32 vcc, v135, v122
	v_cvt_pk_bf16_f32 v106, v106, s0
	v_add_u32_e32 v119, s2, v111
	v_cndmask_b32_e64 v104, v104, 0, vcc
	v_cndmask_b32_e64 v106, v106, 0, vcc
	ds_write_b16 v119, v104
	v_add_u32_e32 v104, s68, v111
	v_or_b32_e32 v134, 3, v123
	ds_write_b16 v104, v106
	v_add_u32_e32 v106, 0xd8, v109
	v_cvt_pk_bf16_f32 v104, v127, s0
	v_cmp_gt_u32_e32 vcc, v134, v122
	v_add_lshl_u32 v111, v106, v122, 1
	v_add_u32_e32 v119, s91, v111
	v_cndmask_b32_e32 v104, 0, v104, vcc
	ds_write_b16 v119, v104
	v_add_u32_e32 v119, 0x330, v116
	v_cndmask_b32_e32 v104, 0, v159, vcc
	v_add_u32_e32 v103, v103, v119
	ds_write_b32 v103, v104
	v_cvt_pk_bf16_f32 v103, v151, s0
	v_cmp_lt_u32_e32 vcc, v134, v122
	v_cvt_pk_bf16_f32 v104, v107, s0
	v_add_u32_e32 v107, s2, v111
	v_cndmask_b32_e64 v103, v103, 0, vcc
	v_mfma_f32_16x16x32_bf16 v[152:155], v[168:171], v[164:167], v[160:163]
	v_cndmask_b32_e64 v104, v104, 0, vcc
	ds_write_b16 v107, v103
	v_add_u32_e32 v103, s68, v111
	v_mfma_f32_16x16x32_bf16 v[112:115], v[168:171], v[140:143], v[112:115]
	ds_write_b16 v103, v104
	v_cvt_pk_bf16_f32 v103, v144, s0
	v_cmp_gt_u32_e32 vcc, v123, v130
	v_add_lshl_u32 v104, v109, v130, 1
	v_add_u32_e32 v107, s91, v104
	v_cndmask_b32_e32 v103, 0, v103, vcc
	ds_write_b16 v107, v103
	v_cndmask_b32_e32 v98, 0, v98, vcc
	v_add_u32_e32 v103, v124, v116
	ds_write_b32 v103, v98 offset:64
	v_cvt_pk_bf16_f32 v98, v152, s0
	v_cmp_lt_u32_e32 vcc, v123, v130
	v_cvt_pk_bf16_f32 v107, v112, s0
	v_add_u32_e32 v109, s2, v104
	v_cndmask_b32_e64 v98, v98, 0, vcc
	v_cndmask_b32_e64 v107, v107, 0, vcc
	ds_write_b16 v109, v98
	v_add_u32_e32 v98, s68, v104
	ds_write_b16 v98, v107
	v_cvt_pk_bf16_f32 v98, v145, s0
	v_add_lshl_u32 v104, v108, v130, 1
	v_cndmask_b32_e64 v98, v98, 0, vcc
	v_add_u32_e32 v107, s91, v104
	ds_write_b16 v107, v98
	v_cndmask_b32_e64 v98, v99, 0, vcc
	v_add_u32_e32 v108, v124, v117
	ds_write_b32 v108, v98 offset:64
	v_cvt_pk_bf16_f32 v98, v153, s0
	v_cmp_lt_u32_e32 vcc, v136, v130
	v_cvt_pk_bf16_f32 v99, v113, s0
	v_add_u32_e32 v107, s2, v104
	v_cndmask_b32_e64 v98, v98, 0, vcc
	v_cndmask_b32_e64 v99, v99, 0, vcc
	ds_write_b16 v107, v98
	v_add_u32_e32 v98, s68, v104
	ds_write_b16 v98, v99
	v_cvt_pk_bf16_f32 v98, v146, s0
	v_cmp_gt_u32_e32 vcc, v135, v130
	v_add_lshl_u32 v99, v105, v130, 1
	v_add_u32_e32 v104, s91, v99
	v_cndmask_b32_e32 v98, 0, v98, vcc
	ds_write_b16 v104, v98
	v_cndmask_b32_e32 v98, 0, v100, vcc
	v_add_u32_e32 v109, v124, v118
	ds_write_b32 v109, v98 offset:64
	v_cvt_pk_bf16_f32 v98, v154, s0
	v_cmp_lt_u32_e32 vcc, v135, v130
	v_cvt_pk_bf16_f32 v100, v114, s0
	v_add_u32_e32 v104, s2, v99
	v_cndmask_b32_e64 v98, v98, 0, vcc
	v_cndmask_b32_e64 v100, v100, 0, vcc
	ds_write_b16 v104, v98
	v_add_u32_e32 v98, s68, v99
	ds_write_b16 v98, v100
	v_cvt_pk_bf16_f32 v98, v147, s0
	v_cmp_gt_u32_e32 vcc, v134, v130
	v_add_lshl_u32 v99, v106, v130, 1
	v_add_u32_e32 v100, s91, v99
	v_cndmask_b32_e32 v98, 0, v98, vcc
	ds_write_b16 v100, v98
	v_cndmask_b32_e32 v98, 0, v101, vcc
	v_add_u32_e32 v111, v124, v119
	ds_write_b32 v111, v98 offset:64
	v_cvt_pk_bf16_f32 v98, v155, s0
	v_cmp_lt_u32_e32 vcc, v134, v130
	v_cvt_pk_bf16_f32 v100, v115, s0
	v_add_u32_e32 v101, s2, v99
	v_cndmask_b32_e64 v98, v98, 0, vcc
	v_cndmask_b32_e64 v100, v100, 0, vcc
	ds_write_b16 v101, v98
	v_add_u32_e32 v98, s68, v99
	v_add3_u32 v112, s91, v131, v190
	ds_write_b16 v98, v100
	s_waitcnt lgkmcnt(0)
; #define LAS __attribute__((address_space(3)))
; #define ZACC(a) do { a[0] = (f32x4){0.f, 0.f, 0.f, 0.f}; a[1] = (f32x4){0.f, 0.f, 0.f, 0.f}; } while (0)
; __device__ __forceinline__ void rwkv_phase_a(const Ctx& C) {
;     ...
;         {
;             f32x4 x1[2]; ZACC(x1);
;             mmb(x1, BM_(7), BM_(4), mrow, nc0, q);
; #pragma unroll
;             for (int i = 0; i < 2; ++i)
; #pragma unroll
;                 for (int j = 0; j < 4; ++j) { const int r = mt * 16 + 4 * q + j, cc = nc0 + 16 * i; FM(1)[r * MS + cc] = x1[i][j]; }
;             if (tid < 64) {
;                 const int blk = tid >> 4, col = tid & 15; const LAS float* L = FM(0) + (blk * 16) * MS + blk * 16;
;                 float x[16];
; #pragma unroll
;                 for (int r = 0; r < 16; ++r) {
;                     float a = (r == col) ? 1.f : 0.f;
; #pragma unroll
;                     for (int s2 = 0; s2 < r; ++s2) a -= L[r * MS + s2] * x[s2];
;                     x[r] = a;
;                 }
; #pragma unroll
;                 for (int r = 0; r < 16; ++r) DI[(blk * 16 + r) * 20 + col] = x[r];
;             }
	s_barrier
	ds_read_b128 v[98:101], v112
	ds_read_b128 v[104:107], v133
	ds_read_b128 v[112:115], v112 offset:64
	ds_read_b128 v[116:119], v133 offset:64
	ds_read_b128 v[126:129], v133 offset:2304
	ds_read_b128 v[140:143], v133 offset:2368
	s_waitcnt vmcnt(8)
	v_perm_b32 v205, v231, v208, s1
	v_perm_b32 v200, v237, v195, s1
	v_perm_b32 v199, v239, v238, s1
	v_perm_b32 v204, v242, v236, s1
	v_perm_b32 v203, v244, v243, s1
	v_perm_b32 v198, v246, v245, s1
	v_perm_b32 v206, v248, v249, s1
	v_perm_b32 v195, v251, v250, s1
	v_perm_b32 v202, v191, v1, s1
	v_perm_b32 v191, v197, v252, s1
	v_perm_b32 v1, v240, v241, s1
	v_perm_b32 v207, v207, v247, s1
	v_perm_b32 v208, v232, v233, s1
	s_waitcnt lgkmcnt(4)
	v_mfma_f32_16x16x32_bf16 v[104:107], v[98:101], v[104:107], 0
	v_add_u32_e32 v103, 0x4400, v103
	v_cmp_gt_i32_e32 vcc, 64, v210
	s_waitcnt lgkmcnt(1)
	v_mfma_f32_16x16x32_bf16 v[98:101], v[98:101], v[126:129], 0
	v_mfma_f32_16x16x32_bf16 v[104:107], v[112:115], v[116:119], v[104:107]
	s_waitcnt lgkmcnt(0)
	v_mfma_f32_16x16x32_bf16 v[98:101], v[112:115], v[140:143], v[98:101]
	s_nop 7
	ds_write2_b32 v103, v104, v98 offset1:16
	v_add_u32_e32 v98, 0x4400, v108
	ds_write2_b32 v98, v105, v99 offset1:16
	v_add_u32_e32 v98, 0x4400, v109
	ds_write2_b32 v98, v106, v100 offset1:16
	v_add_u32_e32 v98, 0x4400, v111
	ds_write2_b32 v98, v107, v101 offset1:16
	s_and_saveexec_b64 s[22:23], vcc
	s_cbranch_execz .LBB0_741
	v_and_b32_e32 v98, -16, v210
	v_mul_lo_u32 v121, v98, s39
	v_lshl_add_u32 v121, v98, 2, v121
	s_movk_i32 s21, 0x50
	ds_read_b128 v[140:143], v121 offset:272
	ds_read_b128 v[144:147], v121 offset:544
	ds_read_b128 v[148:151], v121 offset:816
	ds_read_b128 v[152:155], v121 offset:1088
	ds_read_b128 v[156:159], v121 offset:1360
	ds_read_b128 v[160:163], v121 offset:1376
	ds_read_b128 v[164:167], v121 offset:1632
	ds_read_b128 v[168:171], v121 offset:1648
	ds_read_b128 v[172:175], v121 offset:1904
	ds_read_b128 v[176:179], v121 offset:1920
	ds_read_b128 v[180:183], v121 offset:2176
	ds_read_b128 v[228:231], v121 offset:2192
	v_cmp_eq_u32_e32 vcc, 0, v209
	v_cmp_eq_u32_e64 s[14:15], 1, v209
	s_nop 0
	v_cndmask_b32_e64 v99, 0, 1.0, vcc
	v_cndmask_b32_e64 v100, 0, 1.0, s[14:15]
	v_cmp_eq_u32_e32 vcc, 2, v209
	v_cmp_eq_u32_e64 s[14:15], 3, v209
	s_nop 0
	v_cndmask_b32_e64 v103, 0, 1.0, vcc
	v_cndmask_b32_e64 v104, 0, 1.0, s[14:15]
	v_cmp_eq_u32_e32 vcc, 4, v209
	v_cmp_eq_u32_e64 s[14:15], 5, v209
	s_nop 0
	v_cndmask_b32_e64 v105, 0, 1.0, vcc
	v_cndmask_b32_e64 v106, 0, 1.0, s[14:15]
	v_cmp_eq_u32_e32 vcc, 6, v209
	v_cmp_eq_u32_e64 s[14:15], 7, v209
	s_nop 0
	v_cndmask_b32_e64 v107, 0, 1.0, vcc
	v_cndmask_b32_e64 v108, 0, 1.0, s[14:15]
	v_cmp_eq_u32_e32 vcc, 8, v209
	v_cmp_eq_u32_e64 s[14:15], 9, v209
	s_nop 0
	v_cndmask_b32_e64 v109, 0, 1.0, vcc
	v_cndmask_b32_e64 v111, 0, 1.0, s[14:15]
	v_cmp_eq_u32_e32 vcc, 10, v209
	v_cmp_eq_u32_e64 s[14:15], 11, v209
	s_nop 0
	v_cndmask_b32_e64 v112, 0, 1.0, vcc
	v_cndmask_b32_e64 v113, 0, 1.0, s[14:15]
	v_cmp_eq_u32_e32 vcc, 12, v209
	v_cmp_eq_u32_e64 s[14:15], 13, v209
	s_nop 0
	v_cndmask_b32_e64 v118, 0, 1.0, vcc
	v_cndmask_b32_e64 v119, 0, 1.0, s[14:15]
	v_cmp_eq_u32_e32 vcc, 14, v209
	v_cmp_eq_u32_e64 s[14:15], 15, v209
	s_nop 0
	v_cndmask_b32_e64 v120, 0, 1.0, vcc
	v_cndmask_b32_e64 v101, 0, 1.0, s[14:15]
	s_waitcnt lgkmcnt(6)
	v_fma_f32 v100, -v99, v140, v100
	v_fma_f32 v103, -v99, v144, v103
	v_fma_f32 v104, -v99, v148, v104
	v_fma_f32 v105, -v99, v152, v105
	v_fma_f32 v106, -v99, v156, v106
	v_fma_f32 v103, -v100, v145, v103
	v_fma_f32 v104, -v100, v149, v104
	v_fma_f32 v105, -v100, v153, v105
	v_fma_f32 v106, -v100, v157, v106
	v_fma_f32 v104, -v103, v150, v104
	v_fma_f32 v105, -v103, v154, v105
	v_fma_f32 v106, -v103, v158, v106
	v_fma_f32 v105, -v104, v155, v105
	v_fma_f32 v106, -v104, v159, v106
	v_fma_f32 v106, -v105, v160, v106
	ds_read_b128 v[140:143], v121 offset:2448
	ds_read_b128 v[144:147], v121 offset:2464
	ds_read_b128 v[148:151], v121 offset:2480
	ds_read_b128 v[152:155], v121 offset:2720
	ds_read_b128 v[156:159], v121 offset:2736
	ds_read_b128 v[160:163], v121 offset:2752
	ds_read_b128 v[232:235], v121 offset:2992
	ds_read_b128 v[236:239], v121 offset:3008
	ds_read_b128 v[240:243], v121 offset:3024
	s_waitcnt lgkmcnt(9)
	v_fma_f32 v107, -v99, v164, v107
	v_fma_f32 v108, -v99, v172, v108
	v_fma_f32 v109, -v99, v180, v109
	v_fma_f32 v107, -v100, v165, v107
	v_fma_f32 v108, -v100, v173, v108
	v_fma_f32 v109, -v100, v181, v109
	v_fma_f32 v107, -v103, v166, v107
	v_fma_f32 v108, -v103, v174, v108
	v_fma_f32 v109, -v103, v182, v109
	v_fma_f32 v107, -v104, v167, v107
	v_fma_f32 v108, -v104, v175, v108
	v_fma_f32 v109, -v104, v183, v109
	v_fma_f32 v107, -v105, v168, v107
	v_fma_f32 v108, -v105, v176, v108
	v_fma_f32 v109, -v105, v228, v109
	v_fma_f32 v107, -v106, v169, v107
	v_fma_f32 v108, -v106, v177, v108
	v_fma_f32 v109, -v106, v229, v109
	v_fma_f32 v108, -v107, v178, v108
	v_fma_f32 v109, -v107, v230, v109
	v_fma_f32 v109, -v108, v231, v109
	s_waitcnt lgkmcnt(0)
; #define LAS __attribute__((address_space(3)))
; __device__ __forceinline__ void rwkv_phase_a(const Ctx& C) {
;     ...
;                 const int blk = tid >> 4, col = tid & 15; const LAS float* L = FM(0) + (blk * 16) * MS + blk * 16;
;                 float x[16];
; #pragma unroll
;                 for (int r = 0; r < 16; ++r) {
;                     float a = (r == col) ? 1.f : 0.f;
; #pragma unroll
;                     for (int s2 = 0; s2 < r; ++s2) a -= L[r * MS + s2] * x[s2];
;                     x[r] = a;
;                 }
; #pragma unroll
;                 for (int r = 0; r < 16; ++r) DI[(blk * 16 + r) * 20 + col] = x[r];
	ds_read_b128 v[164:167], v121 offset:3264
	ds_read_b128 v[168:171], v121 offset:3280
	ds_read_b128 v[172:175], v121 offset:3296
	ds_read_b128 v[176:179], v121 offset:3536
	ds_read_b128 v[180:183], v121 offset:3552
	ds_read_b128 v[228:231], v121 offset:3568
	ds_read_b128 v[244:247], v121 offset:3584
	v_fma_f32 v111, -v99, v140, v111
	v_fma_f32 v112, -v99, v152, v112
	v_fma_f32 v113, -v99, v232, v113
	v_fma_f32 v111, -v100, v141, v111
	v_fma_f32 v112, -v100, v153, v112
	v_fma_f32 v113, -v100, v233, v113
	v_fma_f32 v111, -v103, v142, v111
	v_fma_f32 v112, -v103, v154, v112
	v_fma_f32 v113, -v103, v234, v113
	v_fma_f32 v111, -v104, v143, v111
	v_fma_f32 v112, -v104, v155, v112
	v_fma_f32 v113, -v104, v235, v113
	v_fma_f32 v111, -v105, v144, v111
	v_fma_f32 v112, -v105, v156, v112
	v_fma_f32 v113, -v105, v236, v113
	v_fma_f32 v111, -v106, v145, v111
	v_fma_f32 v112, -v106, v157, v112
	v_fma_f32 v113, -v106, v237, v113
	v_fma_f32 v111, -v107, v146, v111
	v_fma_f32 v112, -v107, v158, v112
	v_fma_f32 v113, -v107, v238, v113
	v_fma_f32 v111, -v108, v147, v111
	v_fma_f32 v112, -v108, v159, v112
	v_fma_f32 v113, -v108, v239, v113
	v_fma_f32 v111, -v109, v148, v111
	v_fma_f32 v112, -v109, v160, v112
	v_fma_f32 v113, -v109, v240, v113
	v_fma_f32 v112, -v111, v161, v112
	v_fma_f32 v113, -v111, v241, v113
	v_fma_f32 v113, -v112, v242, v113
	ds_read_b128 v[140:143], v121 offset:3808
	ds_read_b128 v[144:147], v121 offset:3824
	ds_read_b128 v[148:151], v121 offset:3840
	ds_read_b128 v[152:155], v121 offset:3856
	ds_read_b128 v[156:159], v121 offset:4080
	ds_read_b128 v[160:163], v121 offset:4096
	ds_read_b128 v[232:235], v121 offset:4112
	ds_read_b128 v[236:239], v121 offset:4128
	s_waitcnt lgkmcnt(8)
	v_fma_f32 v118, -v99, v164, v118
	v_fma_f32 v119, -v99, v176, v119
	v_fma_f32 v118, -v100, v165, v118
	v_fma_f32 v119, -v100, v177, v119
	v_fma_f32 v118, -v103, v166, v118
	v_fma_f32 v119, -v103, v178, v119
	v_fma_f32 v118, -v104, v167, v118
	v_fma_f32 v119, -v104, v179, v119
	v_fma_f32 v118, -v105, v168, v118
	v_fma_f32 v119, -v105, v180, v119
	v_fma_f32 v118, -v106, v169, v118
	v_fma_f32 v119, -v106, v181, v119
	v_fma_f32 v118, -v107, v170, v118
	v_fma_f32 v119, -v107, v182, v119
	v_fma_f32 v118, -v108, v171, v118
	v_fma_f32 v119, -v108, v183, v119
	v_fma_f32 v118, -v109, v172, v118
	v_fma_f32 v119, -v109, v228, v119
	v_fma_f32 v118, -v111, v173, v118
	v_fma_f32 v119, -v111, v229, v119
	v_fma_f32 v118, -v112, v174, v118
	v_fma_f32 v119, -v112, v230, v119
	v_fma_f32 v118, -v113, v175, v118
	v_fma_f32 v119, -v113, v231, v119
	v_fma_f32 v119, -v118, v244, v119
	s_waitcnt lgkmcnt(0)
	v_fma_f32 v120, -v99, v140, v120
	v_fma_f32 v101, -v99, v156, v101
	v_fma_f32 v120, -v100, v141, v120
	v_fma_f32 v101, -v100, v157, v101
	v_fma_f32 v120, -v103, v142, v120
	v_fma_f32 v101, -v103, v158, v101
	v_fma_f32 v120, -v104, v143, v120
	v_fma_f32 v101, -v104, v159, v101
	v_fma_f32 v120, -v105, v144, v120
	v_fma_f32 v101, -v105, v160, v101
	v_fma_f32 v120, -v106, v145, v120
	v_fma_f32 v101, -v106, v161, v101
	v_fma_f32 v120, -v107, v146, v120
	v_fma_f32 v101, -v107, v162, v101
	v_fma_f32 v120, -v108, v147, v120
	v_fma_f32 v101, -v108, v163, v101
	v_fma_f32 v120, -v109, v148, v120
	v_fma_f32 v101, -v109, v232, v101
	v_fma_f32 v120, -v111, v149, v120
	v_fma_f32 v101, -v111, v233, v101
	v_fma_f32 v120, -v112, v150, v120
	v_fma_f32 v101, -v112, v234, v101
	v_fma_f32 v120, -v113, v151, v120
	v_fma_f32 v101, -v113, v235, v101
	v_fma_f32 v120, -v118, v152, v120
	v_fma_f32 v101, -v118, v236, v101
	v_fma_f32 v120, -v119, v153, v120
	v_fma_f32 v101, -v119, v237, v101
	v_fma_f32 v101, -v120, v238, v101
	v_lshl_add_u32 v114, v209, 2, s69
	v_mad_u64_u32 v[116:117], s[14:15], v98, s21, v[114:115]
	v_add_u32_e32 v98, 0x200, v116
	ds_write2_b32 v116, v99, v100 offset1:20
	ds_write2_b32 v116, v103, v104 offset0:40 offset1:60
	ds_write2_b32 v116, v105, v106 offset0:80 offset1:100
	ds_write2_b32 v116, v107, v108 offset0:120 offset1:140
	ds_write2_b32 v116, v109, v111 offset0:160 offset1:180
	ds_write2_b32 v116, v112, v113 offset0:200 offset1:220
	ds_write2_b32 v98, v118, v119 offset0:112 offset1:132
	ds_write_b32 v116, v120 offset:1120
	v_or_b32_e32 v98, 15, v210
	v_mad_u64_u32 v[98:99], s[14:15], v98, s21, v[114:115]
	ds_write_b32 v98, v101
